# strategy 7.4: static s_setprio 1 for waves 0-3 in both GEMM phases, per-phase flips in the main loops deleted (on top of v1)
# speedup vs baseline: 1.0026x; 1.0019x over previous
.LBB0_206:
	s_and_b64 vcc, exec, s[16:17]
	s_cbranch_vccz .LBB0_246
	v_readlane_b32 s12, v246, 26
	v_mov_b32_e32 v4, v220
	v_readlane_b32 s13, v246, 27
	s_andn2_b64 vcc, exec, s[12:13]
	v_readfirstlane_b32 s27, v4
	s_cbranch_vccnz .LBB0_245
	s_cmpk_lt_u32 s27, 0x100
	s_cbranch_scc0 .Lprio_out
	s_setprio 1
.Lprio_out:
	v_lshlrev_b32_e32 v1, 4, v4
	v_add_u32_e32 v3, 0x2000, v1
	v_ashrrev_i32_e32 v2, 31, v3
	v_lshrrev_b32_e32 v2, 22, v2
	v_add_u32_e32 v2, v3, v2
	v_ashrrev_i32_e32 v2, 10, v2
	v_mul_i32_i24_e32 v5, 0x400, v2
	v_sub_u32_e32 v3, v3, v5
	v_lshrrev_b32_e32 v5, 4, v3
	v_bitop3_b32 v5, v5, v3, 32 bitop3:0x6c
	v_ashrrev_i32_e32 v3, 31, v5
	v_lshrrev_b32_e32 v3, 26, v3
	v_readlane_b32 s12, v244, 39
	v_add_u32_e32 v6, v5, v3
	s_waitcnt lgkmcnt(0)
	v_lshlrev_b32_e32 v7, 3, v2
	v_readlane_b32 s13, v244, 40
	v_ashrrev_i32_e32 v3, 6, v6
	v_and_b32_e32 v7, -16, v7
	s_mov_b32 s16, s12
	s_ashr_i32 s17, s12, 31
	v_writelane_b32 v244, s12, 39
	v_add_u32_e32 v7, v3, v7
	v_and_b32_e32 v8, 3, v3
	v_writelane_b32 v244, s13, 40
	s_lshl_b64 s[12:13], s[16:17], 24
	s_mov_b32 s16, 0x7ffe0
	v_lshrrev_b32_e32 v9, 2, v7
	v_lshlrev_b32_e32 v10, 1, v7
	v_and_b32_e32 v6, 0xc0, v6
	v_and_or_b32 v8, v7, s16, v8
	v_and_b32_e32 v9, 4, v9
	v_and_b32_e32 v10, 24, v10
	v_sub_u32_e32 v5, v5, v6
	v_or3_b32 v8, v8, v9, v10
	v_lshlrev_b32_e32 v9, 5, v2
	v_ashrrev_i16_sdwa v5, v224, sext(v5) dst_sel:DWORD dst_unused:UNUSED_PAD src0_sel:DWORD src1_sel:BYTE_0
	v_and_b32_e32 v9, 32, v9
	v_bfe_i32 v5, v5, 0, 16
	v_add_lshl_u32 v6, v9, v5, 1
	v_lshl_add_u32 v130, v8, 13, v6
	v_lshl_add_u32 v132, v7, 13, v6
	v_bfe_i32 v6, v4, 27, 1
	v_lshrrev_b32_e32 v6, 22, v6
	v_add_u32_e32 v6, v1, v6
	v_and_b32_e32 v6, 0xfffffc00, v6
	v_sub_u32_e32 v1, v1, v6
	v_lshrrev_b32_e32 v6, 4, v1
	v_bitop3_b32 v8, v6, v1, 32 bitop3:0x6c
	v_ashrrev_i32_e32 v1, 31, v1
	v_lshrrev_b32_e32 v1, 26, v1
	v_add_u32_e32 v1, v8, v1
	v_ashrrev_i32_e32 v6, 6, v1
	v_ashrrev_i32_e32 v1, 31, v4
	v_lshrrev_b32_e32 v1, 26, v1
	v_add_u32_e32 v1, v4, v1
	v_ashrrev_i32_e32 v7, 6, v1
	v_lshlrev_b32_e32 v1, 3, v7
	v_and_b32_e32 v1, -16, v1
	v_add_u32_e32 v1, v6, v1
	v_and_b32_e32 v9, 3, v6
	v_lshrrev_b32_e32 v10, 2, v1
	v_lshlrev_b32_e32 v11, 1, v1
	v_and_or_b32 v9, v1, s16, v9
	v_and_b32_e32 v10, 4, v10
	v_and_b32_e32 v11, 24, v11
	s_add_u32 s52, s6, s12
	v_or3_b32 v9, v9, v10, v11
	v_mul_i32_i24_e32 v11, 64, v6
	s_addc_u32 s69, s7, s13
	s_ashr_i32 s13, s27, 6
	v_sub_u32_e32 v8, v8, v11
	s_ashr_i32 s12, s27, 8
	s_lshl_b32 s90, s13, 10
	v_lshlrev_b32_e32 v10, 5, v7
	v_ashrrev_i16_sdwa v8, v224, sext(v8) dst_sel:DWORD dst_unused:UNUSED_PAD src0_sel:DWORD src1_sel:BYTE_0
	v_readlane_b32 s16, v245, 41
	v_and_b32_e32 v10, 32, v10
	v_bfe_i32 v8, v8, 0, 16
	v_readlane_b32 s17, v245, 42
	s_add_u32 s46, s52, s16
	v_add_lshl_u32 v10, v10, v8, 1
	s_addc_u32 s47, s69, s17
	s_add_i32 s91, s90, 0
	v_lshl_add_u32 v134, v9, 13, v10
	s_add_i32 m0, s91, 0x10000
	v_readlane_b32 s16, v245, 46
	global_load_lds_dwordx4 v134, s[46:47]
	s_add_i32 m0, s91, 0x12000
	v_lshl_add_u32 v136, v1, 13, v10
	global_load_lds_dwordx4 v130, s[46:47]
	s_mov_b32 m0, s91
	v_readlane_b32 s17, v245, 47
	s_add_i32 s97, s91, 0x2000
	s_nop 3
	global_load_lds_dwordx4 v136, s[16:17]
	s_mov_b32 m0, s97
	s_nop 0
	global_load_lds_dwordx4 v132, s[16:17]
	s_add_u32 s16, s46, 0x100000
	s_addc_u32 s17, s47, 0
	s_add_i32 m0, s91, 0x14000
	s_add_i32 s96, s91, 0x4000
	global_load_lds_dwordx4 v134, s[16:17]
	s_add_i32 m0, s91, 0x16000
	s_add_i32 s80, s91, 0x6000
	global_load_lds_dwordx4 v130, s[16:17]
	v_readlane_b32 s16, v245, 48
	s_mov_b32 m0, s96
	v_readlane_b32 s17, v245, 49
	s_cmp_lg_u32 s12, 1
	s_nop 3
	global_load_lds_dwordx4 v136, s[16:17]
	s_mov_b32 m0, s80
	s_nop 0
	global_load_lds_dwordx4 v132, s[16:17]
	s_cbranch_scc1 .LBB0_210
	s_barrier

.LBB0_218:
	s_add_u32 s36, s18, s46
	s_addc_u32 s37, s19, s47
	s_add_u32 s36, s36, 0x100
	s_addc_u32 s37, s37, 0
	s_add_u32 s48, s24, s46
	s_addc_u32 s49, s25, s47
	s_add_i32 s50, 0, 0x10000
	v_add_u32_e32 v160, s50, v146
	ds_read_b128 v[148:151], v160
	ds_read_b128 v[152:155], v160 offset:1024
	ds_read_b128 v[156:159], v160 offset:2048
	ds_read_b128 v[160:163], v160 offset:3072
	s_cmpk_eq_i32 s46, 0x1f00
	s_cselect_b32 s87, s23, s37
	s_cselect_b32 s86, vcc_lo, s36
	s_cselect_b32 s49, s21, s49
	s_cselect_b32 s48, vcc_hi, s48
	v_lshl_add_u64 v[196:197], v[142:143], 0, s[46:47]
	s_add_i32 m0, s91, 0xc000
	ds_read_b128 v[164:167], v147
	ds_read_b128 v[168:171], v147 offset:1024
	ds_read_b128 v[172:175], v147 offset:2048
	ds_read_b128 v[176:179], v147 offset:3072
	ds_read_b128 v[180:183], v147 offset:4096
	ds_read_b128 v[184:187], v147 offset:5120
	ds_read_b128 v[188:191], v147 offset:6144
	ds_read_b128 v[192:195], v147 offset:7168
	global_load_lds_dwordx4 v[196:197], off
	v_lshl_add_u64 v[196:197], v[144:145], 0, s[46:47]
	s_add_i32 m0, s91, 0xe000
	s_nop 0
	global_load_lds_dwordx4 v[196:197], off
	s_waitcnt lgkmcnt(8)
	s_barrier
	s_waitcnt lgkmcnt(0)
	s_waitcnt lgkmcnt(0)
	v_mfma_f32_16x16x32_bf16 v[126:129], v[148:151], v[164:167], v[126:129]
	v_mfma_f32_16x16x32_bf16 v[122:125], v[156:159], v[164:167], v[122:125]
	v_mfma_f32_16x16x32_bf16 v[110:113], v[148:151], v[172:175], v[110:113]
	v_mfma_f32_16x16x32_bf16 v[106:109], v[156:159], v[172:175], v[106:109]
	v_mfma_f32_16x16x32_bf16 v[98:101], v[148:151], v[180:183], v[98:101]
	v_mfma_f32_16x16x32_bf16 v[90:93], v[156:159], v[180:183], v[90:93]
	v_mfma_f32_16x16x32_bf16 v[82:85], v[148:151], v[188:191], v[82:85]
	v_mfma_f32_16x16x32_bf16 v[74:77], v[156:159], v[188:191], v[74:77]
	v_mfma_f32_16x16x32_bf16 v[126:129], v[152:155], v[168:171], v[126:129]
	v_mfma_f32_16x16x32_bf16 v[122:125], v[160:163], v[168:171], v[122:125]
	v_mfma_f32_16x16x32_bf16 v[110:113], v[152:155], v[176:179], v[110:113]
	v_mfma_f32_16x16x32_bf16 v[106:109], v[160:163], v[176:179], v[106:109]
	v_mfma_f32_16x16x32_bf16 v[98:101], v[152:155], v[184:187], v[98:101]
	v_mfma_f32_16x16x32_bf16 v[90:93], v[160:163], v[184:187], v[90:93]
	v_mfma_f32_16x16x32_bf16 v[82:85], v[152:155], v[192:195], v[82:85]
	v_mfma_f32_16x16x32_bf16 v[74:77], v[160:163], v[192:195], v[74:77]
	s_barrier
	s_add_i32 s31, 0, 0x14000
	v_add_u32_e32 v200, s31, v146
	s_add_i32 s36, s50, s90
	ds_read_b128 v[196:199], v200
	ds_read_b128 v[216:219], v200 offset:1024
	ds_read_b128 v[232:235], v200 offset:2048
	ds_read_b128 v[236:239], v200 offset:3072
	v_lshl_add_u64 v[200:201], s[48:49], 0, v[134:135]
	s_mov_b32 m0, s36
	v_lshl_add_u64 v[204:205], s[48:49], 0, v[130:131]
	global_load_lds_dwordx4 v[200:201], off
	s_add_i32 m0, s36, 0x2000
	s_nop 0
	global_load_lds_dwordx4 v[204:205], off
	s_barrier
	s_waitcnt lgkmcnt(0)
	s_waitcnt lgkmcnt(0)
	v_mfma_f32_16x16x32_bf16 v[118:121], v[196:199], v[164:167], v[118:121]
	v_mfma_f32_16x16x32_bf16 v[114:117], v[232:235], v[164:167], v[114:117]
	v_mfma_f32_16x16x32_bf16 v[102:105], v[196:199], v[172:175], v[102:105]
	v_mfma_f32_16x16x32_bf16 v[94:97], v[232:235], v[172:175], v[94:97]
	v_mfma_f32_16x16x32_bf16 v[86:89], v[196:199], v[180:183], v[86:89]
	v_mfma_f32_16x16x32_bf16 v[78:81], v[232:235], v[180:183], v[78:81]
	v_mfma_f32_16x16x32_bf16 v[70:73], v[196:199], v[188:191], v[70:73]
	v_mfma_f32_16x16x32_bf16 v[66:69], v[232:235], v[188:191], v[66:69]
	v_mfma_f32_16x16x32_bf16 v[118:121], v[216:219], v[168:171], v[118:121]
	v_mfma_f32_16x16x32_bf16 v[114:117], v[236:239], v[168:171], v[114:117]
	v_mfma_f32_16x16x32_bf16 v[102:105], v[216:219], v[176:179], v[102:105]
	v_mfma_f32_16x16x32_bf16 v[94:97], v[236:239], v[176:179], v[94:97]
	v_mfma_f32_16x16x32_bf16 v[86:89], v[216:219], v[184:187], v[86:89]
	v_mfma_f32_16x16x32_bf16 v[78:81], v[236:239], v[184:187], v[78:81]
	v_mfma_f32_16x16x32_bf16 v[70:73], v[216:219], v[192:195], v[70:73]
	v_mfma_f32_16x16x32_bf16 v[66:69], v[236:239], v[192:195], v[66:69]
	s_mov_b32 m0, s91
	v_lshl_add_u64 v[240:241], s[86:87], 0, v[136:137]
	s_barrier
	ds_read_b128 v[164:167], v147 offset:16384
	ds_read_b128 v[168:171], v147 offset:17408
	ds_read_b128 v[172:175], v147 offset:18432
	ds_read_b128 v[176:179], v147 offset:19456
	ds_read_b128 v[180:183], v147 offset:20480
	ds_read_b128 v[184:187], v147 offset:21504
	ds_read_b128 v[188:191], v147 offset:22528
	ds_read_b128 v[192:195], v147 offset:23552
	global_load_lds_dwordx4 v[240:241], off
	v_lshl_add_u64 v[242:243], s[86:87], 0, v[132:133]
	s_mov_b32 m0, s97
	s_nop 0
	global_load_lds_dwordx4 v[242:243], off
	s_barrier
	s_waitcnt lgkmcnt(0)
	s_waitcnt lgkmcnt(0)
	v_mfma_f32_16x16x32_bf16 v[62:65], v[148:151], v[164:167], v[62:65]
	v_mfma_f32_16x16x32_bf16 v[58:61], v[156:159], v[164:167], v[58:61]
	v_mfma_f32_16x16x32_bf16 v[50:53], v[148:151], v[172:175], v[50:53]
	v_mfma_f32_16x16x32_bf16 v[42:45], v[156:159], v[172:175], v[42:45]
	v_mfma_f32_16x16x32_bf16 v[34:37], v[148:151], v[180:183], v[34:37]
	v_mfma_f32_16x16x32_bf16 v[26:29], v[156:159], v[180:183], v[26:29]
	v_mfma_f32_16x16x32_bf16 v[18:21], v[148:151], v[188:191], v[18:21]
	v_mfma_f32_16x16x32_bf16 v[10:13], v[156:159], v[188:191], v[10:13]
	v_mfma_f32_16x16x32_bf16 v[62:65], v[152:155], v[168:171], v[62:65]
	v_mfma_f32_16x16x32_bf16 v[58:61], v[160:163], v[168:171], v[58:61]
	v_mfma_f32_16x16x32_bf16 v[50:53], v[152:155], v[176:179], v[50:53]
	v_mfma_f32_16x16x32_bf16 v[42:45], v[160:163], v[176:179], v[42:45]
	v_mfma_f32_16x16x32_bf16 v[34:37], v[152:155], v[184:187], v[34:37]
	v_mfma_f32_16x16x32_bf16 v[26:29], v[160:163], v[184:187], v[26:29]
	v_mfma_f32_16x16x32_bf16 v[18:21], v[152:155], v[192:195], v[18:21]
	v_mfma_f32_16x16x32_bf16 v[10:13], v[160:163], v[192:195], v[10:13]
	s_barrier
	s_add_u32 s36, s48, 0x100000
	s_addc_u32 s37, s49, 0
	s_add_i32 s31, s31, s90
	v_lshl_add_u64 v[148:149], s[36:37], 0, v[134:135]
	s_mov_b32 m0, s31
	s_nop 0
	global_load_lds_dwordx4 v[148:149], off
	v_lshl_add_u64 v[148:149], s[36:37], 0, v[130:131]
	s_add_i32 m0, s31, 0x2000
	s_nop 0
	global_load_lds_dwordx4 v[148:149], off
	s_waitcnt vmcnt(6)
	s_barrier
	v_mfma_f32_16x16x32_bf16 v[54:57], v[196:199], v[164:167], v[54:57]
	v_mfma_f32_16x16x32_bf16 v[46:49], v[232:235], v[164:167], v[46:49]
	v_mfma_f32_16x16x32_bf16 v[38:41], v[196:199], v[172:175], v[38:41]
	v_mfma_f32_16x16x32_bf16 v[30:33], v[232:235], v[172:175], v[30:33]
	v_mfma_f32_16x16x32_bf16 v[22:25], v[196:199], v[180:183], v[22:25]
	v_mfma_f32_16x16x32_bf16 v[14:17], v[232:235], v[180:183], v[14:17]
	v_mfma_f32_16x16x32_bf16 v[6:9], v[196:199], v[188:191], v[6:9]
	v_mfma_f32_16x16x32_bf16 v[2:5], v[232:235], v[188:191], v[2:5]
	v_mfma_f32_16x16x32_bf16 v[54:57], v[216:219], v[168:171], v[54:57]
	v_mfma_f32_16x16x32_bf16 v[46:49], v[236:239], v[168:171], v[46:49]
	v_mfma_f32_16x16x32_bf16 v[38:41], v[216:219], v[176:179], v[38:41]
	v_mfma_f32_16x16x32_bf16 v[30:33], v[236:239], v[176:179], v[30:33]
	v_mfma_f32_16x16x32_bf16 v[22:25], v[216:219], v[184:187], v[22:25]
	v_mfma_f32_16x16x32_bf16 v[14:17], v[236:239], v[184:187], v[14:17]
	v_mfma_f32_16x16x32_bf16 v[6:9], v[216:219], v[192:195], v[6:9]
	v_mfma_f32_16x16x32_bf16 v[2:5], v[236:239], v[192:195], v[2:5]
	s_add_i32 s31, 0, 0x18000
	v_add_u32_e32 v160, s31, v146
	s_barrier
	ds_read_b128 v[148:151], v160
	ds_read_b128 v[152:155], v160 offset:1024
	ds_read_b128 v[156:159], v160 offset:2048
	ds_read_b128 v[160:163], v160 offset:3072
	s_add_u32 s36, s86, 0x100000
	s_addc_u32 s37, s87, 0
	s_mov_b32 m0, s96
	v_lshl_add_u64 v[196:197], s[36:37], 0, v[136:137]
	ds_read_b128 v[164:167], v147 offset:32768
	ds_read_b128 v[168:171], v147 offset:33792
	ds_read_b128 v[172:175], v147 offset:34816
	ds_read_b128 v[176:179], v147 offset:35840
	ds_read_b128 v[180:183], v147 offset:36864
	ds_read_b128 v[184:187], v147 offset:37888
	ds_read_b128 v[188:191], v147 offset:38912
	ds_read_b128 v[192:195], v147 offset:39936
	global_load_lds_dwordx4 v[196:197], off
	v_lshl_add_u64 v[196:197], s[36:37], 0, v[132:133]
	s_mov_b32 m0, s80
	s_nop 0
	global_load_lds_dwordx4 v[196:197], off
	s_waitcnt lgkmcnt(8)
	s_barrier
	s_waitcnt lgkmcnt(0)
	s_waitcnt lgkmcnt(0)
	v_mfma_f32_16x16x32_bf16 v[126:129], v[148:151], v[164:167], v[126:129]
	v_mfma_f32_16x16x32_bf16 v[122:125], v[156:159], v[164:167], v[122:125]
	v_mfma_f32_16x16x32_bf16 v[110:113], v[148:151], v[172:175], v[110:113]
	v_mfma_f32_16x16x32_bf16 v[106:109], v[156:159], v[172:175], v[106:109]
	v_mfma_f32_16x16x32_bf16 v[98:101], v[148:151], v[180:183], v[98:101]
	v_mfma_f32_16x16x32_bf16 v[90:93], v[156:159], v[180:183], v[90:93]
	v_mfma_f32_16x16x32_bf16 v[82:85], v[148:151], v[188:191], v[82:85]
	v_mfma_f32_16x16x32_bf16 v[74:77], v[156:159], v[188:191], v[74:77]
	v_mfma_f32_16x16x32_bf16 v[126:129], v[152:155], v[168:171], v[126:129]
	v_mfma_f32_16x16x32_bf16 v[122:125], v[160:163], v[168:171], v[122:125]
	v_mfma_f32_16x16x32_bf16 v[110:113], v[152:155], v[176:179], v[110:113]
	v_mfma_f32_16x16x32_bf16 v[106:109], v[160:163], v[176:179], v[106:109]
	v_mfma_f32_16x16x32_bf16 v[98:101], v[152:155], v[184:187], v[98:101]
	v_mfma_f32_16x16x32_bf16 v[90:93], v[160:163], v[184:187], v[90:93]
	v_mfma_f32_16x16x32_bf16 v[82:85], v[152:155], v[192:195], v[82:85]
	v_mfma_f32_16x16x32_bf16 v[74:77], v[160:163], v[192:195], v[74:77]
	s_barrier
	s_add_i32 s50, 0, 0x1c000
	s_add_i32 s31, s31, s90
	v_add_u32_e32 v203, s50, v146
	v_lshl_add_u64 v[200:201], v[200:201], 0, s[14:15]
	s_mov_b32 m0, s31
	ds_read_b128 v[196:199], v203
	ds_read_b128 v[216:219], v203 offset:1024
	ds_read_b128 v[232:235], v203 offset:2048
	ds_read_b128 v[236:239], v203 offset:3072
	global_load_lds_dwordx4 v[200:201], off
	v_lshl_add_u64 v[200:201], v[204:205], 0, s[14:15]
	s_add_i32 m0, s31, 0x2000
	s_nop 0
	global_load_lds_dwordx4 v[200:201], off
	s_barrier
	s_waitcnt lgkmcnt(0)
	s_waitcnt lgkmcnt(0)
	v_mfma_f32_16x16x32_bf16 v[118:121], v[196:199], v[164:167], v[118:121]
	v_mfma_f32_16x16x32_bf16 v[114:117], v[232:235], v[164:167], v[114:117]
	v_mfma_f32_16x16x32_bf16 v[102:105], v[196:199], v[172:175], v[102:105]
	v_mfma_f32_16x16x32_bf16 v[94:97], v[232:235], v[172:175], v[94:97]
	v_mfma_f32_16x16x32_bf16 v[86:89], v[196:199], v[180:183], v[86:89]
	v_mfma_f32_16x16x32_bf16 v[78:81], v[232:235], v[180:183], v[78:81]
	v_mfma_f32_16x16x32_bf16 v[70:73], v[196:199], v[188:191], v[70:73]
	v_mfma_f32_16x16x32_bf16 v[66:69], v[232:235], v[188:191], v[66:69]
	v_mfma_f32_16x16x32_bf16 v[118:121], v[216:219], v[168:171], v[118:121]
	v_mfma_f32_16x16x32_bf16 v[114:117], v[236:239], v[168:171], v[114:117]
	v_mfma_f32_16x16x32_bf16 v[102:105], v[216:219], v[176:179], v[102:105]
	v_mfma_f32_16x16x32_bf16 v[94:97], v[236:239], v[176:179], v[94:97]
	v_mfma_f32_16x16x32_bf16 v[86:89], v[216:219], v[184:187], v[86:89]
	v_mfma_f32_16x16x32_bf16 v[78:81], v[236:239], v[184:187], v[78:81]
	v_mfma_f32_16x16x32_bf16 v[70:73], v[216:219], v[192:195], v[70:73]
	v_mfma_f32_16x16x32_bf16 v[66:69], v[236:239], v[192:195], v[66:69]
	s_mov_b32 m0, s81
	v_lshl_add_u64 v[200:201], v[240:241], 0, s[14:15]
	s_barrier
	ds_read_b128 v[164:167], v147 offset:49152
	ds_read_b128 v[168:171], v147 offset:50176
	ds_read_b128 v[172:175], v147 offset:51200
	ds_read_b128 v[176:179], v147 offset:52224
	ds_read_b128 v[180:183], v147 offset:53248
	ds_read_b128 v[184:187], v147 offset:54272
	ds_read_b128 v[188:191], v147 offset:55296
	ds_read_b128 v[192:195], v147 offset:56320
	global_load_lds_dwordx4 v[200:201], off
	v_lshl_add_u64 v[200:201], v[242:243], 0, s[14:15]
	s_mov_b32 m0, s33
	s_nop 0
	global_load_lds_dwordx4 v[200:201], off
	s_barrier
	s_waitcnt lgkmcnt(0)
	s_waitcnt lgkmcnt(0)
	v_mfma_f32_16x16x32_bf16 v[62:65], v[148:151], v[164:167], v[62:65]
	v_mfma_f32_16x16x32_bf16 v[58:61], v[156:159], v[164:167], v[58:61]
	v_mfma_f32_16x16x32_bf16 v[50:53], v[148:151], v[172:175], v[50:53]
	v_mfma_f32_16x16x32_bf16 v[42:45], v[156:159], v[172:175], v[42:45]
	v_mfma_f32_16x16x32_bf16 v[34:37], v[148:151], v[180:183], v[34:37]
	v_mfma_f32_16x16x32_bf16 v[26:29], v[156:159], v[180:183], v[26:29]
	v_mfma_f32_16x16x32_bf16 v[18:21], v[148:151], v[188:191], v[18:21]
	v_mfma_f32_16x16x32_bf16 v[10:13], v[156:159], v[188:191], v[10:13]
	v_mfma_f32_16x16x32_bf16 v[62:65], v[152:155], v[168:171], v[62:65]
	v_mfma_f32_16x16x32_bf16 v[58:61], v[160:163], v[168:171], v[58:61]
	v_mfma_f32_16x16x32_bf16 v[50:53], v[152:155], v[176:179], v[50:53]
	v_mfma_f32_16x16x32_bf16 v[42:45], v[160:163], v[176:179], v[42:45]
	v_mfma_f32_16x16x32_bf16 v[34:37], v[152:155], v[184:187], v[34:37]
	v_mfma_f32_16x16x32_bf16 v[26:29], v[160:163], v[184:187], v[26:29]
	v_mfma_f32_16x16x32_bf16 v[18:21], v[152:155], v[192:195], v[18:21]
	v_mfma_f32_16x16x32_bf16 v[10:13], v[160:163], v[192:195], v[10:13]
	s_barrier
	s_add_u32 s36, s48, 0x100080
	s_addc_u32 s37, s49, 0
	s_add_i32 s31, s50, s90
	v_lshl_add_u64 v[148:149], s[36:37], 0, v[134:135]
	s_mov_b32 m0, s31
	s_nop 0
	global_load_lds_dwordx4 v[148:149], off
	v_lshl_add_u64 v[148:149], s[36:37], 0, v[130:131]
	s_add_i32 m0, s31, 0x2000
	s_nop 0
	global_load_lds_dwordx4 v[148:149], off
	s_waitcnt vmcnt(6)
	s_barrier
	v_mfma_f32_16x16x32_bf16 v[54:57], v[196:199], v[164:167], v[54:57]
	v_mfma_f32_16x16x32_bf16 v[46:49], v[232:235], v[164:167], v[46:49]
	v_mfma_f32_16x16x32_bf16 v[38:41], v[196:199], v[172:175], v[38:41]
	v_mfma_f32_16x16x32_bf16 v[30:33], v[232:235], v[172:175], v[30:33]
	v_mfma_f32_16x16x32_bf16 v[22:25], v[196:199], v[180:183], v[22:25]
	v_mfma_f32_16x16x32_bf16 v[14:17], v[232:235], v[180:183], v[14:17]
	v_mfma_f32_16x16x32_bf16 v[6:9], v[196:199], v[188:191], v[6:9]
	v_mfma_f32_16x16x32_bf16 v[2:5], v[232:235], v[188:191], v[2:5]
	v_mfma_f32_16x16x32_bf16 v[54:57], v[216:219], v[168:171], v[54:57]
	v_mfma_f32_16x16x32_bf16 v[46:49], v[236:239], v[168:171], v[46:49]
	v_mfma_f32_16x16x32_bf16 v[38:41], v[216:219], v[176:179], v[38:41]
	v_mfma_f32_16x16x32_bf16 v[30:33], v[236:239], v[176:179], v[30:33]
	v_mfma_f32_16x16x32_bf16 v[22:25], v[216:219], v[184:187], v[22:25]
	v_mfma_f32_16x16x32_bf16 v[14:17], v[236:239], v[184:187], v[14:17]
	v_mfma_f32_16x16x32_bf16 v[6:9], v[216:219], v[192:195], v[6:9]
	v_mfma_f32_16x16x32_bf16 v[2:5], v[236:239], v[192:195], v[2:5]
	s_add_i32 s13, s13, 2
	s_add_u32 s46, s46, 0x100
	s_addc_u32 s47, s47, 0
	s_cmp_gt_u32 s13, 61
	s_barrier
	s_cbranch_scc0 .LBB0_218
	s_add_u32 s24, s24, 0xffffff00
	s_addc_u32 s25, s25, -1
	s_andn2_b64 vcc, exec, s[40:41]
	s_cbranch_vccnz .LBB0_221
	v_mov_b32_e32 v2, 0
	s_mov_b32 s16, s20
	s_mov_b32 s30, s22
	s_mov_b64 s[18:19], s[44:45]
	s_mov_b32 s12, s83
	v_mov_b32_e32 v3, v2
	v_mov_b32_e32 v4, v2
	v_mov_b32_e32 v5, v2
	v_mov_b32_e32 v6, v2
	v_mov_b32_e32 v7, v2
	v_mov_b32_e32 v8, v2
	v_mov_b32_e32 v9, v2
	v_mov_b32_e32 v14, v2
	v_mov_b32_e32 v15, v2
	v_mov_b32_e32 v16, v2
	v_mov_b32_e32 v17, v2
	v_mov_b32_e32 v22, v2
	v_mov_b32_e32 v23, v2
	v_mov_b32_e32 v24, v2
	v_mov_b32_e32 v25, v2
	v_mov_b32_e32 v30, v2
	v_mov_b32_e32 v31, v2
	v_mov_b32_e32 v32, v2
	v_mov_b32_e32 v33, v2
	v_mov_b32_e32 v38, v2
	v_mov_b32_e32 v39, v2
	v_mov_b32_e32 v40, v2
	v_mov_b32_e32 v41, v2
	v_mov_b32_e32 v46, v2
	v_mov_b32_e32 v47, v2
	v_mov_b32_e32 v48, v2
	v_mov_b32_e32 v49, v2
	v_mov_b32_e32 v54, v2
	v_mov_b32_e32 v55, v2
	v_mov_b32_e32 v56, v2
	v_mov_b32_e32 v57, v2
	v_mov_b32_e32 v10, v2
	v_mov_b32_e32 v11, v2
	v_mov_b32_e32 v12, v2
	v_mov_b32_e32 v13, v2
	v_mov_b32_e32 v18, v2
	v_mov_b32_e32 v19, v2
	v_mov_b32_e32 v20, v2
	v_mov_b32_e32 v21, v2
	v_mov_b32_e32 v26, v2
	v_mov_b32_e32 v27, v2
	v_mov_b32_e32 v28, v2
	v_mov_b32_e32 v29, v2
	v_mov_b32_e32 v34, v2
	v_mov_b32_e32 v35, v2
	v_mov_b32_e32 v36, v2
	v_mov_b32_e32 v37, v2
	v_mov_b32_e32 v42, v2
	v_mov_b32_e32 v43, v2
	v_mov_b32_e32 v44, v2
	v_mov_b32_e32 v45, v2
	v_mov_b32_e32 v50, v2
	v_mov_b32_e32 v51, v2
	v_mov_b32_e32 v52, v2
	v_mov_b32_e32 v53, v2
	v_mov_b32_e32 v58, v2
	v_mov_b32_e32 v59, v2
	v_mov_b32_e32 v60, v2
	v_mov_b32_e32 v61, v2
	v_mov_b32_e32 v62, v2
	v_mov_b32_e32 v63, v2
	v_mov_b32_e32 v64, v2
	v_mov_b32_e32 v65, v2
	v_mov_b32_e32 v66, v2
	v_mov_b32_e32 v67, v2
	v_mov_b32_e32 v68, v2
	v_mov_b32_e32 v69, v2
	v_mov_b32_e32 v70, v2
	v_mov_b32_e32 v71, v2
	v_mov_b32_e32 v72, v2
	v_mov_b32_e32 v73, v2
	v_mov_b32_e32 v78, v2
	v_mov_b32_e32 v79, v2
	v_mov_b32_e32 v80, v2
	v_mov_b32_e32 v81, v2
	v_mov_b32_e32 v86, v2
	v_mov_b32_e32 v87, v2
	v_mov_b32_e32 v88, v2
	v_mov_b32_e32 v89, v2
	v_mov_b32_e32 v94, v2
	v_mov_b32_e32 v95, v2
	v_mov_b32_e32 v96, v2
	v_mov_b32_e32 v97, v2
	v_mov_b32_e32 v102, v2
	v_mov_b32_e32 v103, v2
	v_mov_b32_e32 v104, v2
	v_mov_b32_e32 v105, v2
	v_mov_b32_e32 v114, v2
	v_mov_b32_e32 v115, v2
	v_mov_b32_e32 v116, v2
	v_mov_b32_e32 v117, v2
	v_mov_b32_e32 v118, v2
	v_mov_b32_e32 v119, v2
	v_mov_b32_e32 v120, v2
	v_mov_b32_e32 v121, v2
	v_mov_b32_e32 v74, v2
	v_mov_b32_e32 v75, v2
	v_mov_b32_e32 v76, v2
	v_mov_b32_e32 v77, v2
	v_mov_b32_e32 v82, v2
	v_mov_b32_e32 v83, v2
	v_mov_b32_e32 v84, v2
	v_mov_b32_e32 v85, v2
	v_mov_b32_e32 v90, v2
	v_mov_b32_e32 v91, v2
	v_mov_b32_e32 v92, v2
	v_mov_b32_e32 v93, v2
	v_mov_b32_e32 v98, v2
	v_mov_b32_e32 v99, v2
	v_mov_b32_e32 v100, v2
	v_mov_b32_e32 v101, v2
	v_mov_b32_e32 v106, v2
	v_mov_b32_e32 v107, v2
	v_mov_b32_e32 v108, v2
	v_mov_b32_e32 v109, v2
	v_mov_b32_e32 v110, v2
	v_mov_b32_e32 v111, v2
	v_mov_b32_e32 v112, v2
	v_mov_b32_e32 v113, v2
	v_mov_b32_e32 v122, v2
	v_mov_b32_e32 v123, v2
	v_mov_b32_e32 v124, v2
	v_mov_b32_e32 v125, v2
	v_mov_b32_e32 v126, v2
	v_mov_b32_e32 v127, v2
	v_mov_b32_e32 v128, v2
	v_mov_b32_e32 v129, v2
	s_branch .LBB0_222

.LBB0_224:
	s_setprio 0
	s_waitcnt vmcnt(0)
	s_cmpk_gt_u32 s27, 0xff
	s_cbranch_scc1 .LBB0_226
	s_barrier

.LBB0_251:
	s_or_b64 exec, exec, s[16:17]
	v_readlane_b32 s12, v244, 39
	v_readlane_b32 s13, v244, 40
	s_ashr_i32 s13, s12, 31
	v_mov_b32_e32 v8, v220
	v_writelane_b32 v244, s12, 39
	s_waitcnt lgkmcnt(0)
	s_barrier
	s_and_b64 vcc, exec, s[38:39]
	v_readfirstlane_b32 s47, v8
	v_writelane_b32 v244, s13, 40
	s_cbranch_vccnz .LBB0_295
	s_cmpk_lt_u32 s47, 0x100
	s_cbranch_scc0 .Lprio_in
	s_setprio 1
.Lprio_in:
	v_lshlrev_b32_e32 v1, 4, v8
	v_add_u32_e32 v3, 0x2000, v1
	v_ashrrev_i32_e32 v2, 31, v3
	v_lshrrev_b32_e32 v2, 22, v2
	v_add_u32_e32 v2, v3, v2
	v_ashrrev_i32_e32 v2, 10, v2
	v_mul_i32_i24_e32 v4, 0x400, v2
	v_sub_u32_e32 v3, v3, v4
	v_lshrrev_b32_e32 v4, 4, v3
	v_bitop3_b32 v4, v4, v3, 32 bitop3:0x6c
	v_ashrrev_i32_e32 v3, 31, v4
	v_lshrrev_b32_e32 v3, 26, v3
	s_ashr_i32 s13, s47, 6
	v_readlane_b32 s18, v244, 39
	v_add_u32_e32 v5, v4, v3
	v_lshlrev_b32_e32 v6, 3, v2
	s_ashr_i32 s12, s47, 8
	s_lshl_b32 s48, s13, 10
	s_mul_i32 s17, s18, 0x3400000
	v_ashrrev_i32_e32 v3, 6, v5
	v_and_b32_e32 v6, -16, v6
	s_mul_hi_i32 s16, s18, 0x3400000
	s_add_u32 s49, s76, s17
	v_add_u32_e32 v6, v3, v6
	s_addc_u32 s52, s77, s16
	v_and_b32_e32 v7, 3, v3
	s_mov_b32 s16, 0xfffe0
	v_lshrrev_b32_e32 v9, 2, v6
	v_lshlrev_b32_e32 v10, 1, v6
	v_and_b32_e32 v5, 0xc0, v5
	v_and_or_b32 v7, v6, s16, v7
	v_and_b32_e32 v9, 4, v9
	v_and_b32_e32 v10, 24, v10
	v_sub_u32_e32 v4, v4, v5
	v_or3_b32 v7, v7, v9, v10
	v_lshlrev_b32_e32 v9, 5, v2
	v_ashrrev_i16_sdwa v4, v224, sext(v4) dst_sel:DWORD dst_unused:UNUSED_PAD src0_sel:DWORD src1_sel:BYTE_0
	v_and_b32_e32 v9, 32, v9
	v_bfe_i32 v4, v4, 0, 16
	v_add_lshl_u32 v5, v9, v4, 1
	v_lshl_add_u32 v130, v7, 12, v5
	v_lshl_add_u32 v132, v6, 12, v5
	v_bfe_i32 v5, v8, 27, 1
	v_lshrrev_b32_e32 v5, 22, v5
	v_add_u32_e32 v5, v1, v5
	v_and_b32_e32 v5, 0xfffffc00, v5
	v_sub_u32_e32 v1, v1, v5
	v_lshrrev_b32_e32 v5, 4, v1
	v_bitop3_b32 v7, v5, v1, 32 bitop3:0x6c
	v_ashrrev_i32_e32 v1, 31, v1
	v_lshrrev_b32_e32 v1, 26, v1
	v_add_u32_e32 v1, v7, v1
	v_ashrrev_i32_e32 v5, 6, v1
	v_ashrrev_i32_e32 v1, 31, v8
	v_lshrrev_b32_e32 v1, 26, v1
	v_add_u32_e32 v1, v8, v1
	v_ashrrev_i32_e32 v6, 6, v1
	v_lshlrev_b32_e32 v1, 3, v6
	v_and_b32_e32 v1, -16, v1
	v_add_u32_e32 v1, v5, v1
	v_and_b32_e32 v9, 3, v5
	v_lshrrev_b32_e32 v10, 2, v1
	v_lshlrev_b32_e32 v11, 1, v1
	v_and_or_b32 v9, v1, s16, v9
	v_and_b32_e32 v10, 4, v10
	v_and_b32_e32 v11, 24, v11
	v_or3_b32 v9, v9, v10, v11
	v_mul_i32_i24_e32 v11, 64, v5
	v_sub_u32_e32 v7, v7, v11
	v_lshlrev_b32_e32 v10, 5, v6
	v_ashrrev_i16_sdwa v7, v224, sext(v7) dst_sel:DWORD dst_unused:UNUSED_PAD src0_sel:DWORD src1_sel:BYTE_0
	v_readlane_b32 s16, v245, 50
	v_and_b32_e32 v10, 32, v10
	v_bfe_i32 v7, v7, 0, 16
	v_readlane_b32 s17, v245, 51
	s_add_u32 s42, s49, s16
	v_add_lshl_u32 v10, v10, v7, 1
	s_addc_u32 s43, s52, s17
	s_add_i32 s69, s48, 0
	v_lshl_add_u32 v134, v9, 12, v10
	s_add_i32 m0, s69, 0x10000
	v_readlane_b32 s16, v245, 54
	global_load_lds_dwordx4 v134, s[42:43]
	s_add_i32 m0, s69, 0x12000
	v_lshl_add_u32 v136, v1, 12, v10
	global_load_lds_dwordx4 v130, s[42:43]
	s_mov_b32 m0, s69
	v_readlane_b32 s17, v245, 55
	s_add_i32 s86, s69, 0x2000
	v_readlane_b32 s19, v244, 40
	s_nop 2
	global_load_lds_dwordx4 v136, s[16:17]
	s_mov_b32 m0, s86
	s_nop 0
	global_load_lds_dwordx4 v132, s[16:17]
	s_add_u32 s16, s42, 0x80000
	s_addc_u32 s17, s43, 0
	s_add_i32 m0, s69, 0x14000
	s_add_i32 s87, s69, 0x4000
	global_load_lds_dwordx4 v134, s[16:17]
	s_add_i32 m0, s69, 0x16000
	s_add_i32 s90, s69, 0x6000
	global_load_lds_dwordx4 v130, s[16:17]
	v_readlane_b32 s16, v245, 56
	s_mov_b32 m0, s87
	v_readlane_b32 s17, v245, 57
	s_cmp_lg_u32 s12, 1
	s_nop 3
	global_load_lds_dwordx4 v136, s[16:17]
	s_mov_b32 m0, s90
	s_nop 0
	global_load_lds_dwordx4 v132, s[16:17]
	s_cbranch_scc1 .LBB0_254
	s_barrier

.LBB0_259:
	s_add_u32 s13, s40, 0xfff80080
	s_addc_u32 s36, s41, -1
	s_add_i32 s37, 0, 0x10000
	v_add_u32_e32 v146, s37, v147
	ds_read_b128 v[142:145], v146
	ds_read_b128 v[152:155], v146 offset:1024
	ds_read_b128 v[156:159], v146 offset:2048
	ds_read_b128 v[160:163], v146 offset:3072
	s_cmp_eq_u32 s81, 28
	s_cselect_b32 s45, s19, s36
	s_cselect_b32 s44, s24, s13
	s_cselect_b32 s43, s17, s80
	s_cselect_b32 s42, s25, s33
	v_lshl_add_u64 v[196:197], s[40:41], 0, v[138:139]
	s_add_i32 m0, s69, 0xc000
	ds_read_b128 v[164:167], v150
	ds_read_b128 v[168:171], v150 offset:1024
	ds_read_b128 v[172:175], v150 offset:2048
	ds_read_b128 v[176:179], v150 offset:3072
	ds_read_b128 v[180:183], v150 offset:4096
	ds_read_b128 v[184:187], v150 offset:5120
	ds_read_b128 v[188:191], v150 offset:6144
	ds_read_b128 v[192:195], v150 offset:7168
	global_load_lds_dwordx4 v[196:197], off
	v_lshl_add_u64 v[196:197], s[40:41], 0, v[140:141]
	s_add_i32 m0, s69, 0xe000
	s_nop 0
	global_load_lds_dwordx4 v[196:197], off
	s_waitcnt lgkmcnt(8)
	s_barrier
	s_waitcnt lgkmcnt(0)
	s_waitcnt lgkmcnt(0)
	v_mfma_f32_16x16x32_bf16 v[126:129], v[142:145], v[164:167], v[126:129]
	v_mfma_f32_16x16x32_bf16 v[122:125], v[156:159], v[164:167], v[122:125]
	v_mfma_f32_16x16x32_bf16 v[110:113], v[142:145], v[172:175], v[110:113]
	v_mfma_f32_16x16x32_bf16 v[106:109], v[156:159], v[172:175], v[106:109]
	v_mfma_f32_16x16x32_bf16 v[94:97], v[142:145], v[180:183], v[94:97]
	v_mfma_f32_16x16x32_bf16 v[90:93], v[156:159], v[180:183], v[90:93]
	v_mfma_f32_16x16x32_bf16 v[78:81], v[142:145], v[188:191], v[78:81]
	v_mfma_f32_16x16x32_bf16 v[74:77], v[156:159], v[188:191], v[74:77]
	v_mfma_f32_16x16x32_bf16 v[126:129], v[152:155], v[168:171], v[126:129]
	v_mfma_f32_16x16x32_bf16 v[122:125], v[160:163], v[168:171], v[122:125]
	v_mfma_f32_16x16x32_bf16 v[110:113], v[152:155], v[176:179], v[110:113]
	v_mfma_f32_16x16x32_bf16 v[106:109], v[160:163], v[176:179], v[106:109]
	v_mfma_f32_16x16x32_bf16 v[94:97], v[152:155], v[184:187], v[94:97]
	v_mfma_f32_16x16x32_bf16 v[90:93], v[160:163], v[184:187], v[90:93]
	v_mfma_f32_16x16x32_bf16 v[78:81], v[152:155], v[192:195], v[78:81]
	v_mfma_f32_16x16x32_bf16 v[74:77], v[160:163], v[192:195], v[74:77]
	s_barrier
	s_add_i32 s13, 0, 0x14000
	s_add_i32 s36, s37, s48
	v_add_u32_e32 v146, s13, v147
	v_lshl_add_u64 v[204:205], s[42:43], 0, v[134:135]
	s_mov_b32 m0, s36
	ds_read_b128 v[196:199], v146
	ds_read_b128 v[200:203], v146 offset:1024
	ds_read_b128 v[216:219], v146 offset:2048
	ds_read_b128 v[232:235], v146 offset:3072
	global_load_lds_dwordx4 v[204:205], off
	v_lshl_add_u64 v[236:237], s[42:43], 0, v[130:131]
	s_add_i32 m0, s36, 0x2000
	s_nop 0
	global_load_lds_dwordx4 v[236:237], off
	s_barrier
	s_waitcnt lgkmcnt(0)
	s_waitcnt lgkmcnt(0)
	v_mfma_f32_16x16x32_bf16 v[118:121], v[196:199], v[164:167], v[118:121]
	v_mfma_f32_16x16x32_bf16 v[114:117], v[216:219], v[164:167], v[114:117]
	v_mfma_f32_16x16x32_bf16 v[102:105], v[196:199], v[172:175], v[102:105]
	v_mfma_f32_16x16x32_bf16 v[98:101], v[216:219], v[172:175], v[98:101]
	v_mfma_f32_16x16x32_bf16 v[86:89], v[196:199], v[180:183], v[86:89]
	v_mfma_f32_16x16x32_bf16 v[82:85], v[216:219], v[180:183], v[82:85]
	v_mfma_f32_16x16x32_bf16 v[70:73], v[196:199], v[188:191], v[70:73]
	v_mfma_f32_16x16x32_bf16 v[66:69], v[216:219], v[188:191], v[66:69]
	v_mfma_f32_16x16x32_bf16 v[118:121], v[200:203], v[168:171], v[118:121]
	v_mfma_f32_16x16x32_bf16 v[114:117], v[232:235], v[168:171], v[114:117]
	v_mfma_f32_16x16x32_bf16 v[102:105], v[200:203], v[176:179], v[102:105]
	v_mfma_f32_16x16x32_bf16 v[98:101], v[232:235], v[176:179], v[98:101]
	v_mfma_f32_16x16x32_bf16 v[86:89], v[200:203], v[184:187], v[86:89]
	v_mfma_f32_16x16x32_bf16 v[82:85], v[232:235], v[184:187], v[82:85]
	v_mfma_f32_16x16x32_bf16 v[70:73], v[200:203], v[192:195], v[70:73]
	v_mfma_f32_16x16x32_bf16 v[66:69], v[232:235], v[192:195], v[66:69]
	s_mov_b32 m0, s69
	v_lshl_add_u64 v[238:239], s[44:45], 0, v[136:137]
	s_barrier
	ds_read_b128 v[164:167], v150 offset:16384
	ds_read_b128 v[168:171], v150 offset:17408
	ds_read_b128 v[172:175], v150 offset:18432
	ds_read_b128 v[176:179], v150 offset:19456
	ds_read_b128 v[180:183], v150 offset:20480
	ds_read_b128 v[184:187], v150 offset:21504
	ds_read_b128 v[188:191], v150 offset:22528
	ds_read_b128 v[192:195], v150 offset:23552
	global_load_lds_dwordx4 v[238:239], off
	v_lshl_add_u64 v[240:241], s[44:45], 0, v[132:133]
	s_mov_b32 m0, s86
	s_nop 0
	global_load_lds_dwordx4 v[240:241], off
	s_barrier
	s_waitcnt lgkmcnt(0)
	s_waitcnt lgkmcnt(0)
	v_mfma_f32_16x16x32_bf16 v[62:65], v[142:145], v[164:167], v[62:65]
	v_mfma_f32_16x16x32_bf16 v[58:61], v[156:159], v[164:167], v[58:61]
	v_mfma_f32_16x16x32_bf16 v[46:49], v[142:145], v[172:175], v[46:49]
	v_mfma_f32_16x16x32_bf16 v[42:45], v[156:159], v[172:175], v[42:45]
	v_mfma_f32_16x16x32_bf16 v[30:33], v[142:145], v[180:183], v[30:33]
	v_mfma_f32_16x16x32_bf16 v[26:29], v[156:159], v[180:183], v[26:29]
	v_mfma_f32_16x16x32_bf16 v[14:17], v[142:145], v[188:191], v[14:17]
	v_mfma_f32_16x16x32_bf16 v[10:13], v[156:159], v[188:191], v[10:13]
	v_mfma_f32_16x16x32_bf16 v[62:65], v[152:155], v[168:171], v[62:65]
	v_mfma_f32_16x16x32_bf16 v[58:61], v[160:163], v[168:171], v[58:61]
	v_mfma_f32_16x16x32_bf16 v[46:49], v[152:155], v[176:179], v[46:49]
	v_mfma_f32_16x16x32_bf16 v[42:45], v[160:163], v[176:179], v[42:45]
	v_mfma_f32_16x16x32_bf16 v[30:33], v[152:155], v[184:187], v[30:33]
	v_mfma_f32_16x16x32_bf16 v[26:29], v[160:163], v[184:187], v[26:29]
	v_mfma_f32_16x16x32_bf16 v[14:17], v[152:155], v[192:195], v[14:17]
	v_mfma_f32_16x16x32_bf16 v[10:13], v[160:163], v[192:195], v[10:13]
	s_barrier
	s_add_u32 s96, s42, 0x80000
	s_addc_u32 s97, s43, 0
	s_add_i32 s13, s13, s48
	v_lshl_add_u64 v[142:143], s[96:97], 0, v[134:135]
	s_mov_b32 m0, s13
	s_nop 0
	global_load_lds_dwordx4 v[142:143], off
	v_lshl_add_u64 v[142:143], s[96:97], 0, v[130:131]
	s_add_i32 m0, s13, 0x2000
	s_nop 0
	global_load_lds_dwordx4 v[142:143], off
	s_waitcnt vmcnt(6)
	s_barrier
	v_mfma_f32_16x16x32_bf16 v[54:57], v[196:199], v[164:167], v[54:57]
	v_mfma_f32_16x16x32_bf16 v[50:53], v[216:219], v[164:167], v[50:53]
	v_mfma_f32_16x16x32_bf16 v[38:41], v[196:199], v[172:175], v[38:41]
	v_mfma_f32_16x16x32_bf16 v[34:37], v[216:219], v[172:175], v[34:37]
	v_mfma_f32_16x16x32_bf16 v[22:25], v[196:199], v[180:183], v[22:25]
	v_mfma_f32_16x16x32_bf16 v[18:21], v[216:219], v[180:183], v[18:21]
	v_mfma_f32_16x16x32_bf16 v[6:9], v[196:199], v[188:191], v[6:9]
	v_mfma_f32_16x16x32_bf16 v[2:5], v[216:219], v[188:191], v[2:5]
	v_mfma_f32_16x16x32_bf16 v[54:57], v[200:203], v[168:171], v[54:57]
	v_mfma_f32_16x16x32_bf16 v[50:53], v[232:235], v[168:171], v[50:53]
	v_mfma_f32_16x16x32_bf16 v[38:41], v[200:203], v[176:179], v[38:41]
	v_mfma_f32_16x16x32_bf16 v[34:37], v[232:235], v[176:179], v[34:37]
	v_mfma_f32_16x16x32_bf16 v[22:25], v[200:203], v[184:187], v[22:25]
	v_mfma_f32_16x16x32_bf16 v[18:21], v[232:235], v[184:187], v[18:21]
	v_mfma_f32_16x16x32_bf16 v[6:9], v[200:203], v[192:195], v[6:9]
	v_mfma_f32_16x16x32_bf16 v[2:5], v[232:235], v[192:195], v[2:5]
	s_add_i32 s13, 0, 0x18000
	v_add_u32_e32 v146, s13, v147
	s_barrier
	ds_read_b128 v[142:145], v146
	ds_read_b128 v[152:155], v146 offset:1024
	ds_read_b128 v[156:159], v146 offset:2048
	ds_read_b128 v[160:163], v146 offset:3072
	s_add_u32 s44, s44, 0x80000
	s_addc_u32 s45, s45, 0
	s_mov_b32 m0, s87
	v_lshl_add_u64 v[196:197], s[44:45], 0, v[136:137]
	ds_read_b128 v[164:167], v150 offset:32768
	ds_read_b128 v[168:171], v150 offset:33792
	ds_read_b128 v[172:175], v150 offset:34816
	ds_read_b128 v[176:179], v150 offset:35840
	ds_read_b128 v[180:183], v150 offset:36864
	ds_read_b128 v[184:187], v150 offset:37888
	ds_read_b128 v[188:191], v150 offset:38912
	ds_read_b128 v[192:195], v150 offset:39936
	global_load_lds_dwordx4 v[196:197], off
	v_lshl_add_u64 v[196:197], s[44:45], 0, v[132:133]
	s_mov_b32 m0, s90
	s_nop 0
	global_load_lds_dwordx4 v[196:197], off
	s_waitcnt lgkmcnt(8)
	s_barrier
	s_waitcnt lgkmcnt(0)
	s_waitcnt lgkmcnt(0)
	v_mfma_f32_16x16x32_bf16 v[126:129], v[142:145], v[164:167], v[126:129]
	v_mfma_f32_16x16x32_bf16 v[122:125], v[156:159], v[164:167], v[122:125]
	v_mfma_f32_16x16x32_bf16 v[110:113], v[142:145], v[172:175], v[110:113]
	v_mfma_f32_16x16x32_bf16 v[106:109], v[156:159], v[172:175], v[106:109]
	v_mfma_f32_16x16x32_bf16 v[94:97], v[142:145], v[180:183], v[94:97]
	v_mfma_f32_16x16x32_bf16 v[90:93], v[156:159], v[180:183], v[90:93]
	v_mfma_f32_16x16x32_bf16 v[78:81], v[142:145], v[188:191], v[78:81]
	v_mfma_f32_16x16x32_bf16 v[74:77], v[156:159], v[188:191], v[74:77]
	v_mfma_f32_16x16x32_bf16 v[126:129], v[152:155], v[168:171], v[126:129]
	v_mfma_f32_16x16x32_bf16 v[122:125], v[160:163], v[168:171], v[122:125]
	v_mfma_f32_16x16x32_bf16 v[110:113], v[152:155], v[176:179], v[110:113]
	v_mfma_f32_16x16x32_bf16 v[106:109], v[160:163], v[176:179], v[106:109]
	v_mfma_f32_16x16x32_bf16 v[94:97], v[152:155], v[184:187], v[94:97]
	v_mfma_f32_16x16x32_bf16 v[90:93], v[160:163], v[184:187], v[90:93]
	v_mfma_f32_16x16x32_bf16 v[78:81], v[152:155], v[192:195], v[78:81]
	v_mfma_f32_16x16x32_bf16 v[74:77], v[160:163], v[192:195], v[74:77]
	s_barrier
	s_add_i32 s36, 0, 0x1c000
	s_add_i32 s13, s13, s48
	v_add_u32_e32 v146, s36, v147
	v_lshl_add_u64 v[204:205], v[204:205], 0, s[14:15]
	s_mov_b32 m0, s13
	ds_read_b128 v[196:199], v146
	ds_read_b128 v[200:203], v146 offset:1024
	ds_read_b128 v[216:219], v146 offset:2048
	ds_read_b128 v[232:235], v146 offset:3072
	global_load_lds_dwordx4 v[204:205], off
	v_lshl_add_u64 v[204:205], v[236:237], 0, s[14:15]
	s_add_i32 m0, s13, 0x2000
	s_nop 0
	global_load_lds_dwordx4 v[204:205], off
	s_barrier
	s_waitcnt lgkmcnt(0)
	s_waitcnt lgkmcnt(0)
	v_mfma_f32_16x16x32_bf16 v[118:121], v[196:199], v[164:167], v[118:121]
	v_mfma_f32_16x16x32_bf16 v[114:117], v[216:219], v[164:167], v[114:117]
	v_mfma_f32_16x16x32_bf16 v[102:105], v[196:199], v[172:175], v[102:105]
	v_mfma_f32_16x16x32_bf16 v[98:101], v[216:219], v[172:175], v[98:101]
	v_mfma_f32_16x16x32_bf16 v[86:89], v[196:199], v[180:183], v[86:89]
	v_mfma_f32_16x16x32_bf16 v[82:85], v[216:219], v[180:183], v[82:85]
	v_mfma_f32_16x16x32_bf16 v[70:73], v[196:199], v[188:191], v[70:73]
	v_mfma_f32_16x16x32_bf16 v[66:69], v[216:219], v[188:191], v[66:69]
	v_mfma_f32_16x16x32_bf16 v[118:121], v[200:203], v[168:171], v[118:121]
	v_mfma_f32_16x16x32_bf16 v[114:117], v[232:235], v[168:171], v[114:117]
	v_mfma_f32_16x16x32_bf16 v[102:105], v[200:203], v[176:179], v[102:105]
	v_mfma_f32_16x16x32_bf16 v[98:101], v[232:235], v[176:179], v[98:101]
	v_mfma_f32_16x16x32_bf16 v[86:89], v[200:203], v[184:187], v[86:89]
	v_mfma_f32_16x16x32_bf16 v[82:85], v[232:235], v[184:187], v[82:85]
	v_mfma_f32_16x16x32_bf16 v[70:73], v[200:203], v[192:195], v[70:73]
	v_mfma_f32_16x16x32_bf16 v[66:69], v[232:235], v[192:195], v[66:69]
	s_mov_b32 m0, s91
	v_lshl_add_u64 v[204:205], v[238:239], 0, s[14:15]
	s_barrier
	ds_read_b128 v[164:167], v150 offset:49152
	ds_read_b128 v[168:171], v150 offset:50176
	ds_read_b128 v[172:175], v150 offset:51200
	ds_read_b128 v[176:179], v150 offset:52224
	ds_read_b128 v[180:183], v150 offset:53248
	ds_read_b128 v[184:187], v150 offset:54272
	ds_read_b128 v[188:191], v150 offset:55296
	ds_read_b128 v[192:195], v150 offset:56320
	global_load_lds_dwordx4 v[204:205], off
	v_lshl_add_u64 v[204:205], v[240:241], 0, s[14:15]
	s_mov_b32 m0, s26
	s_nop 0
	global_load_lds_dwordx4 v[204:205], off
	s_barrier
	s_waitcnt lgkmcnt(0)
	s_waitcnt lgkmcnt(0)
	v_mfma_f32_16x16x32_bf16 v[62:65], v[142:145], v[164:167], v[62:65]
	v_mfma_f32_16x16x32_bf16 v[58:61], v[156:159], v[164:167], v[58:61]
	v_mfma_f32_16x16x32_bf16 v[46:49], v[142:145], v[172:175], v[46:49]
	v_mfma_f32_16x16x32_bf16 v[42:45], v[156:159], v[172:175], v[42:45]
	v_mfma_f32_16x16x32_bf16 v[30:33], v[142:145], v[180:183], v[30:33]
	v_mfma_f32_16x16x32_bf16 v[26:29], v[156:159], v[180:183], v[26:29]
	v_mfma_f32_16x16x32_bf16 v[14:17], v[142:145], v[188:191], v[14:17]
	v_mfma_f32_16x16x32_bf16 v[10:13], v[156:159], v[188:191], v[10:13]
	v_mfma_f32_16x16x32_bf16 v[62:65], v[152:155], v[168:171], v[62:65]
	v_mfma_f32_16x16x32_bf16 v[58:61], v[160:163], v[168:171], v[58:61]
	v_mfma_f32_16x16x32_bf16 v[46:49], v[152:155], v[176:179], v[46:49]
	v_mfma_f32_16x16x32_bf16 v[42:45], v[160:163], v[176:179], v[42:45]
	v_mfma_f32_16x16x32_bf16 v[30:33], v[152:155], v[184:187], v[30:33]
	v_mfma_f32_16x16x32_bf16 v[26:29], v[160:163], v[184:187], v[26:29]
	v_mfma_f32_16x16x32_bf16 v[14:17], v[152:155], v[192:195], v[14:17]
	v_mfma_f32_16x16x32_bf16 v[10:13], v[160:163], v[192:195], v[10:13]
	s_barrier
	s_add_u32 s42, s42, 0x80080
	s_addc_u32 s43, s43, 0
	s_add_i32 s13, s36, s48
	v_lshl_add_u64 v[142:143], s[42:43], 0, v[134:135]
	s_mov_b32 m0, s13
	s_nop 0
	global_load_lds_dwordx4 v[142:143], off
	v_lshl_add_u64 v[142:143], s[42:43], 0, v[130:131]
	s_add_i32 m0, s13, 0x2000
	s_nop 0
	global_load_lds_dwordx4 v[142:143], off
	s_waitcnt vmcnt(6)
	s_barrier
	v_mfma_f32_16x16x32_bf16 v[54:57], v[196:199], v[164:167], v[54:57]
	v_mfma_f32_16x16x32_bf16 v[50:53], v[216:219], v[164:167], v[50:53]
	v_mfma_f32_16x16x32_bf16 v[38:41], v[196:199], v[172:175], v[38:41]
	v_mfma_f32_16x16x32_bf16 v[34:37], v[216:219], v[172:175], v[34:37]
	v_mfma_f32_16x16x32_bf16 v[22:25], v[196:199], v[180:183], v[22:25]
	v_mfma_f32_16x16x32_bf16 v[18:21], v[216:219], v[180:183], v[18:21]
	v_mfma_f32_16x16x32_bf16 v[6:9], v[196:199], v[188:191], v[6:9]
	v_mfma_f32_16x16x32_bf16 v[2:5], v[216:219], v[188:191], v[2:5]
	v_mfma_f32_16x16x32_bf16 v[54:57], v[200:203], v[168:171], v[54:57]
	v_mfma_f32_16x16x32_bf16 v[50:53], v[232:235], v[168:171], v[50:53]
	v_mfma_f32_16x16x32_bf16 v[38:41], v[200:203], v[176:179], v[38:41]
	v_mfma_f32_16x16x32_bf16 v[34:37], v[232:235], v[176:179], v[34:37]
	v_mfma_f32_16x16x32_bf16 v[22:25], v[200:203], v[184:187], v[22:25]
	v_mfma_f32_16x16x32_bf16 v[18:21], v[232:235], v[184:187], v[18:21]
	v_mfma_f32_16x16x32_bf16 v[6:9], v[200:203], v[192:195], v[6:9]
	v_mfma_f32_16x16x32_bf16 v[2:5], v[232:235], v[192:195], v[2:5]
	s_add_i32 s81, s81, 2
	s_add_u32 s40, s40, 0x100
	s_addc_u32 s41, s41, 0
	s_add_u32 s33, s33, 0x100
	s_addc_u32 s80, s80, 0
	s_cmp_gt_u32 s81, 29
	s_barrier
	s_cbranch_scc0 .LBB0_259
	s_cmp_lg_u32 s12, s46
	v_lshl_add_u32 v144, s12, 8, v1
	s_cselect_b64 s[42:43], -1, 0
	s_mov_b64 s[24:25], -1
	s_and_b64 vcc, exec, s[42:43]
	v_ashrrev_i32_e32 v145, 31, v144
	s_cbranch_vccz .LBB0_262
	v_lshl_add_u64 v[142:143], v[144:145], 2, s[0:1]
	v_add_co_u32_e32 v152, vcc, 0x8000, v142
	global_load_dword v146, v[142:143], off
	s_nop 0
	v_addc_co_u32_e32 v153, vcc, 0, v143, vcc
	global_load_dword v151, v[152:153], off
	v_add_co_u32_e32 v152, vcc, 0x10000, v142
	s_mov_b64 s[24:25], 0
	s_nop 0
	v_addc_co_u32_e32 v153, vcc, 0, v143, vcc
	s_waitcnt vmcnt(0)
	v_add_f32_e32 v146, 0, v146
	v_add_f32_e32 v146, v146, v151
	global_load_dword v151, v[152:153], off
	v_add_co_u32_e32 v152, vcc, 0x18000, v142
	s_waitcnt vmcnt(0)
	v_add_f32_e32 v146, v146, v151
	v_addc_co_u32_e32 v153, vcc, 0, v143, vcc
	global_load_dword v151, v[152:153], off
	v_add_co_u32_e32 v152, vcc, s5, v142
	s_waitcnt vmcnt(0)
	v_add_f32_e32 v146, v146, v151
	v_addc_co_u32_e32 v153, vcc, 0, v143, vcc
	global_load_dword v151, v[152:153], off
	v_add_co_u32_e32 v152, vcc, 0x28000, v142
	s_waitcnt vmcnt(0)
	v_add_f32_e32 v146, v146, v151
	v_addc_co_u32_e32 v153, vcc, 0, v143, vcc
	global_load_dword v151, v[152:153], off
	v_add_co_u32_e32 v152, vcc, 0x30000, v142
	s_waitcnt vmcnt(0)
	v_add_f32_e32 v146, v146, v151
	v_addc_co_u32_e32 v153, vcc, 0, v143, vcc
	v_add_co_u32_e32 v142, vcc, 0x38000, v142
	global_load_dword v151, v[152:153], off
	s_nop 0
	v_addc_co_u32_e32 v143, vcc, 0, v143, vcc
	global_load_dword v142, v[142:143], off
	s_waitcnt vmcnt(0)
	v_add_f32_e32 v146, v146, v151
	v_add_f32_e32 v142, v146, v142
	v_fmamk_f32 v142, v142, 0x3a000000, v223
	v_cmp_gt_f32_e32 vcc, s4, v142
	v_mul_f32_e32 v143, 0x4b800000, v142
	s_nop 0
	v_cndmask_b32_e32 v142, v142, v143, vcc
	v_rsq_f32_e32 v142, v142
	s_nop 0
	v_mul_f32_e32 v143, 0x45800000, v142
	v_cndmask_b32_e32 v146, v142, v143, vcc

.LBB0_292:
	s_setprio 0
	s_waitcnt vmcnt(0)
	s_cmpk_gt_u32 s47, 0xff
	v_readlane_b32 s30, v244, 33
	v_readlane_b32 s31, v244, 34
	s_cbranch_scc1 .LBB0_294
	s_barrier
